# MLA latent epilogue: all 15 remaining silu(gate) chunks prefetched into v208-237 right after the row base is known, instead of one dependent global load + vmcnt(0) per store step
# speedup vs baseline: 1.0100x; 1.0100x over previous
.LBB0_502:
	s_or_b64 exec, exec, s[16:17]
	v_add_f32_e32 v64, v64, v65
	v_fmac_f32_e32 v64, v186, v96
	v_rcp_f32_e32 v67, v64
	s_lshl_b64 s[14:15], s[14:15], 12
	s_add_u32 s14, s23, s14
	s_addc_u32 s15, s24, s15
	v_mul_f32_e32 v16, v67, v16
	v_mul_f32_e32 v17, v67, v17
	v_cvt_pk_bf16_f32 v80, v16, v17
	v_mul_f32_e32 v16, v67, v18
	v_mul_f32_e32 v17, v67, v19
	v_cvt_pk_bf16_f32 v81, v16, v17
	v_mul_f32_e32 v16, v67, v20
	v_mul_f32_e32 v17, v67, v21
	v_cvt_pk_bf16_f32 v82, v16, v17
	v_mul_f32_e32 v16, v67, v22
	v_mul_f32_e32 v17, v67, v23
	v_cvt_pk_bf16_f32 v83, v16, v17
	v_mul_f32_e32 v16, v67, v24
	v_mul_f32_e32 v17, v67, v25
	v_cvt_pk_bf16_f32 v84, v16, v17
	v_mul_f32_e32 v16, v67, v26
	v_mul_f32_e32 v17, v67, v27
	v_cvt_pk_bf16_f32 v85, v16, v17
	v_mul_f32_e32 v16, v67, v28
	v_mul_f32_e32 v17, v67, v29
	v_cvt_pk_bf16_f32 v86, v16, v17
	v_mul_f32_e32 v16, v67, v30
	v_mul_f32_e32 v17, v67, v31
	v_cvt_pk_bf16_f32 v87, v16, v17
	v_mul_f32_e32 v16, v67, v32
	v_mul_f32_e32 v17, v67, v33
	v_cvt_pk_bf16_f32 v88, v16, v17
	v_mul_f32_e32 v16, v67, v34
	v_mul_f32_e32 v17, v67, v35
	v_cvt_pk_bf16_f32 v89, v16, v17
	v_mul_f32_e32 v16, v67, v36
	v_mul_f32_e32 v17, v67, v37
	v_cvt_pk_bf16_f32 v90, v16, v17
	v_mul_f32_e32 v16, v67, v38
	v_mul_f32_e32 v17, v67, v39
	v_cvt_pk_bf16_f32 v91, v16, v17
	v_mul_f32_e32 v16, v67, v40
	v_mul_f32_e32 v17, v67, v41
	v_cvt_pk_bf16_f32 v92, v16, v17
	v_mul_f32_e32 v16, v67, v42
	v_mul_f32_e32 v17, v67, v43
	v_cvt_pk_bf16_f32 v93, v16, v17
	v_mul_f32_e32 v16, v67, v44
	v_mul_f32_e32 v17, v67, v45
	v_cvt_pk_bf16_f32 v94, v16, v17
	v_mul_f32_e32 v16, v67, v46
	v_mul_f32_e32 v17, v67, v47
	v_cvt_pk_bf16_f32 v95, v16, v17
	v_mul_f32_e32 v16, v67, v48
	v_mul_f32_e32 v17, v67, v49
	v_cvt_pk_bf16_f32 v76, v16, v17
	v_mul_f32_e32 v16, v67, v50
	v_mul_f32_e32 v17, v67, v51
	v_cvt_pk_bf16_f32 v77, v16, v17
	v_mul_f32_e32 v16, v67, v52
	v_mul_f32_e32 v17, v67, v53
	v_cvt_pk_bf16_f32 v78, v16, v17
	v_mul_f32_e32 v16, v67, v54
	v_mul_f32_e32 v17, v67, v55
	v_cvt_pk_bf16_f32 v79, v16, v17
	v_mul_f32_e32 v16, v67, v56
	v_mul_f32_e32 v17, v67, v57
	v_cvt_pk_bf16_f32 v72, v16, v17
	v_mul_f32_e32 v16, v67, v58
	v_mul_f32_e32 v17, v67, v59
	v_cvt_pk_bf16_f32 v73, v16, v17
	v_mul_f32_e32 v16, v67, v60
	v_mul_f32_e32 v17, v67, v61
	v_mul_f32_e32 v0, v67, v0
	v_mul_f32_e32 v1, v67, v1
	v_cvt_pk_bf16_f32 v74, v16, v17
	v_mul_f32_e32 v16, v67, v62
	v_mul_f32_e32 v17, v67, v63
	v_cvt_pk_bf16_f32 v75, v16, v17
	v_cvt_pk_bf16_f32 v68, v0, v1
	v_mul_f32_e32 v0, v67, v2
	v_mul_f32_e32 v1, v67, v3
	v_cvt_pk_bf16_f32 v69, v0, v1
	v_mul_f32_e32 v0, v67, v4
	v_mul_f32_e32 v1, v67, v5
	v_cvt_pk_bf16_f32 v70, v0, v1
	v_mul_f32_e32 v0, v67, v6
	v_mul_f32_e32 v1, v67, v7
	s_lshl_b32 s16, s0, 8
	v_cvt_pk_bf16_f32 v71, v0, v1
	v_mul_f32_e32 v0, v67, v8
	v_mul_f32_e32 v1, v67, v9
	s_add_u32 s14, s14, s16
	v_cvt_pk_bf16_f32 v64, v0, v1
	v_mul_f32_e32 v0, v67, v10
	v_mul_f32_e32 v1, v67, v11
	s_addc_u32 s15, s15, 0
	v_lshl_add_u64 v[208:209], s[14:15], 0, v[154:155]
	v_lshl_add_u64 v[208:209], v[208:209], 0, v[150:151]
	global_load_dwordx2 v[210:211], v[208:209], off offset:32
	global_load_dwordx2 v[212:213], v[208:209], off offset:48
	global_load_dwordx2 v[214:215], v[208:209], off offset:64
	global_load_dwordx2 v[216:217], v[208:209], off offset:80
	global_load_dwordx2 v[218:219], v[208:209], off offset:96
	global_load_dwordx2 v[220:221], v[208:209], off offset:112
	global_load_dwordx2 v[222:223], v[208:209], off offset:128
	global_load_dwordx2 v[224:225], v[208:209], off offset:144
	global_load_dwordx2 v[226:227], v[208:209], off offset:160
	global_load_dwordx2 v[228:229], v[208:209], off offset:176
	global_load_dwordx2 v[230:231], v[208:209], off offset:192
	global_load_dwordx2 v[232:233], v[208:209], off offset:208
	global_load_dwordx2 v[234:235], v[208:209], off offset:224
	global_load_dwordx2 v[236:237], v[208:209], off offset:240
	global_load_dwordx2 v[208:209], v[208:209], off offset:16
	v_cvt_pk_bf16_f32 v65, v0, v1
	v_mul_f32_e32 v0, v67, v12
	v_mul_f32_e32 v1, v67, v13
	s_lshl_b32 s0, s0, 15
	v_cvt_pk_bf16_f32 v66, v0, v1
	v_mul_f32_e32 v0, v67, v14
	v_mul_f32_e32 v1, v67, v15
	v_lshl_add_u64 v[62:63], v[152:153], 0, s[0:1]
	v_cvt_pk_bf16_f32 v67, v0, v1
	global_load_dwordx2 v[0:1], v[62:63], off
	global_load_dwordx2 v[2:3], v[62:63], off offset:16
	global_load_dwordx2 v[16:17], v[62:63], off offset:32
	global_load_dwordx2 v[18:19], v[62:63], off offset:48
	global_load_dwordx2 v[20:21], v[62:63], off offset:64
	global_load_dwordx2 v[22:23], v[62:63], off offset:80
	global_load_dwordx2 v[24:25], v[62:63], off offset:96
	global_load_dwordx2 v[26:27], v[62:63], off offset:112
	global_load_dwordx2 v[28:29], v[62:63], off offset:128
	global_load_dwordx2 v[30:31], v[62:63], off offset:144
	v_add_co_u32_e32 v48, vcc, s36, v62
	s_waitcnt vmcnt(0)
	v_mfma_f32_32x32x16_bf16 v[0:15], v[0:3], v[80:83], 0
	v_addc_co_u32_e32 v49, vcc, 0, v63, vcc
	v_add_co_u32_e32 v138, vcc, s37, v62
	s_add_i32 s41, s41, s60
	s_nop 0
	v_addc_co_u32_e32 v139, vcc, 0, v63, vcc
	v_mfma_f32_32x32x16_bf16 v[0:15], v[16:19], v[84:87], v[0:15]
	global_load_dwordx2 v[16:17], v[62:63], off offset:160
	global_load_dwordx2 v[18:19], v[62:63], off offset:176
	v_add_co_u32_e32 v146, vcc, s40, v62
	s_cmpk_gt_i32 s41, 0x7ff
	s_nop 0
	v_addc_co_u32_e32 v147, vcc, 0, v63, vcc
	v_mfma_f32_32x32x16_bf16 v[0:15], v[20:23], v[88:91], v[0:15]
	global_load_dwordx2 v[20:21], v[62:63], off offset:192
	global_load_dwordx2 v[22:23], v[62:63], off offset:208
	v_mfma_f32_32x32x16_bf16 v[0:15], v[24:27], v[92:95], v[0:15]
	global_load_dwordx2 v[24:25], v[48:49], off
	global_load_dwordx2 v[26:27], v[48:49], off offset:16
	global_load_dwordx2 v[32:33], v[62:63], off offset:224
	global_load_dwordx2 v[34:35], v[62:63], off offset:240
	global_load_dwordx2 v[36:37], v[48:49], off offset:32
	global_load_dwordx2 v[38:39], v[48:49], off offset:48
	global_load_dwordx2 v[40:41], v[48:49], off offset:64
	global_load_dwordx2 v[42:43], v[48:49], off offset:80
	global_load_dwordx2 v[44:45], v[48:49], off offset:96
	global_load_dwordx2 v[46:47], v[48:49], off offset:112
	v_lshl_add_u64 v[62:63], s[14:15], 0, v[154:155]
	v_lshl_add_u64 v[96:97], v[62:63], 0, v[150:151]
	v_mfma_f32_32x32x16_bf16 v[0:15], v[28:31], v[76:79], v[0:15]
	s_waitcnt vmcnt(0)
	v_mfma_f32_32x32x16_bf16 v[0:15], v[16:19], v[72:75], v[0:15]
	v_mfma_f32_32x32x16_bf16 v[0:15], v[20:23], v[68:71], v[0:15]
	v_mfma_f32_32x32x16_bf16 v[0:15], v[32:35], v[64:67], v[0:15]
	global_load_dwordx2 v[32:33], v[138:139], off
	global_load_dwordx2 v[34:35], v[138:139], off offset:16
	global_load_dwordx2 v[50:51], v[138:139], off offset:32
	global_load_dwordx2 v[52:53], v[138:139], off offset:48
	global_load_dwordx2 v[54:55], v[138:139], off offset:64
	global_load_dwordx2 v[56:57], v[138:139], off offset:80
	global_load_dwordx2 v[58:59], v[138:139], off offset:96
	global_load_dwordx2 v[60:61], v[138:139], off offset:112
	global_load_dwordx2 v[98:99], v[146:147], off
	global_load_dwordx2 v[100:101], v[146:147], off offset:16
	global_load_dwordx2 v[102:103], v[146:147], off offset:32
	global_load_dwordx2 v[104:105], v[146:147], off offset:48
	global_load_dwordx2 v[106:107], v[146:147], off offset:64
	global_load_dwordx2 v[108:109], v[146:147], off offset:80
	global_load_dwordx2 v[158:159], v[96:97], off
	v_mfma_f32_32x32x16_bf16 v[16:31], v[24:27], v[80:83], 0
	global_load_dwordx2 v[110:111], v[146:147], off offset:96
	global_load_dwordx2 v[112:113], v[146:147], off offset:112
	global_load_dwordx2 v[114:115], v[48:49], off offset:128
	global_load_dwordx2 v[116:117], v[48:49], off offset:144
	global_load_dwordx2 v[118:119], v[48:49], off offset:160
	global_load_dwordx2 v[120:121], v[48:49], off offset:176
	global_load_dwordx2 v[122:123], v[48:49], off offset:192
	global_load_dwordx2 v[124:125], v[48:49], off offset:208
	global_load_dwordx2 v[126:127], v[48:49], off offset:224
	global_load_dwordx2 v[128:129], v[48:49], off offset:240
	global_load_dwordx2 v[130:131], v[138:139], off offset:128
	global_load_dwordx2 v[132:133], v[138:139], off offset:144
	global_load_dwordx2 v[134:135], v[138:139], off offset:160
	global_load_dwordx2 v[136:137], v[138:139], off offset:176
	v_mfma_f32_32x32x16_bf16 v[16:31], v[36:39], v[84:87], v[16:31]
	v_mfma_f32_32x32x16_bf16 v[16:31], v[40:43], v[88:91], v[16:31]
	v_mfma_f32_32x32x16_bf16 v[16:31], v[44:47], v[92:95], v[16:31]
	s_waitcnt vmcnt(0)
	v_mfma_f32_32x32x16_bf16 v[32:47], v[32:35], v[80:83], 0
	v_mfma_f32_32x32x16_bf16 v[32:47], v[50:53], v[84:87], v[32:47]
	v_mfma_f32_32x32x16_bf16 v[32:47], v[54:57], v[88:91], v[32:47]
	v_mfma_f32_32x32x16_bf16 v[32:47], v[58:61], v[92:95], v[32:47]
	v_mfma_f32_32x32x16_bf16 v[48:63], v[98:101], v[80:83], 0
	global_load_dwordx2 v[80:81], v[138:139], off offset:192
	global_load_dwordx2 v[82:83], v[138:139], off offset:208
	global_load_dwordx2 v[98:99], v[138:139], off offset:224
	global_load_dwordx2 v[100:101], v[138:139], off offset:240
	s_nop 0
	global_load_dwordx2 v[138:139], v[146:147], off offset:128
	global_load_dwordx2 v[140:141], v[146:147], off offset:144
	global_load_dwordx2 v[142:143], v[146:147], off offset:160
	global_load_dwordx2 v[144:145], v[146:147], off offset:176
	v_mfma_f32_32x32x16_bf16 v[48:63], v[102:105], v[84:87], v[48:63]
	global_load_dwordx2 v[84:85], v[146:147], off offset:192
	global_load_dwordx2 v[86:87], v[146:147], off offset:208
	global_load_dwordx2 v[102:103], v[146:147], off offset:224
	global_load_dwordx2 v[104:105], v[146:147], off offset:240
	v_lshlrev_b32_e32 v146, 16, v158
	v_and_b32_e32 v147, 0xffff0000, v158
	v_lshlrev_b32_e32 v158, 16, v159
	v_mul_f32_e32 v0, v0, v146
	v_mul_f32_e32 v1, v1, v147
	v_cvt_pk_bf16_f32 v0, v0, v1
	v_mfma_f32_32x32x16_bf16 v[48:63], v[106:109], v[88:91], v[48:63]
	v_and_b32_e32 v88, 0xffff0000, v159
	v_mul_f32_e32 v1, v2, v158
	v_mul_f32_e32 v2, v3, v88
	v_cvt_pk_bf16_f32 v1, v1, v2
	s_nop 0
	global_store_dwordx2 v[96:97], v[0:1], off
	v_mfma_f32_32x32x16_bf16 v[16:31], v[114:117], v[76:79], v[16:31]
	s_waitcnt vmcnt(1)
	v_lshlrev_b32_e32 v0, 16, v208
	v_and_b32_e32 v1, 0xffff0000, v208
	v_lshlrev_b32_e32 v2, 16, v209
	v_and_b32_e32 v3, 0xffff0000, v209
	v_mul_f32_e32 v0, v4, v0
	v_mul_f32_e32 v1, v5, v1
	v_mul_f32_e32 v2, v6, v2
	v_mul_f32_e32 v3, v7, v3
	v_cvt_pk_bf16_f32 v0, v0, v1
	v_cvt_pk_bf16_f32 v1, v2, v3
	v_mfma_f32_32x32x16_bf16 v[16:31], v[118:121], v[72:75], v[16:31]
	global_store_dwordx2 v[96:97], v[0:1], off offset:16
	v_lshlrev_b32_e32 v0, 16, v210
	v_and_b32_e32 v1, 0xffff0000, v210
	v_lshlrev_b32_e32 v2, 16, v211
	v_and_b32_e32 v3, 0xffff0000, v211
	v_mul_f32_e32 v0, v8, v0
	v_mul_f32_e32 v1, v9, v1
	v_mul_f32_e32 v2, v10, v2
	v_mul_f32_e32 v3, v11, v3
	v_cvt_pk_bf16_f32 v0, v0, v1
	v_cvt_pk_bf16_f32 v1, v2, v3
	v_mfma_f32_32x32x16_bf16 v[16:31], v[122:125], v[68:71], v[16:31]
	global_store_dwordx2 v[96:97], v[0:1], off offset:32
	v_lshlrev_b32_e32 v0, 16, v212
	v_and_b32_e32 v1, 0xffff0000, v212
	v_lshlrev_b32_e32 v2, 16, v213
	v_and_b32_e32 v3, 0xffff0000, v213
	v_mul_f32_e32 v0, v12, v0
	v_mul_f32_e32 v1, v13, v1
	v_mul_f32_e32 v2, v14, v2
	v_mul_f32_e32 v3, v15, v3
	v_cvt_pk_bf16_f32 v0, v0, v1
	v_cvt_pk_bf16_f32 v1, v2, v3
	v_mfma_f32_32x32x16_bf16 v[16:31], v[126:129], v[64:67], v[16:31]
	global_store_dwordx2 v[96:97], v[0:1], off offset:48
	v_lshlrev_b32_e32 v0, 16, v214
	v_and_b32_e32 v1, 0xffff0000, v214
	v_lshlrev_b32_e32 v2, 16, v215
	v_and_b32_e32 v3, 0xffff0000, v215
	s_nop 5
	v_mul_f32_e32 v0, v16, v0
	v_mul_f32_e32 v1, v17, v1
	v_mul_f32_e32 v2, v18, v2
	v_mul_f32_e32 v3, v19, v3
	v_cvt_pk_bf16_f32 v0, v0, v1
	v_cvt_pk_bf16_f32 v1, v2, v3
	v_mfma_f32_32x32x16_bf16 v[32:47], v[130:133], v[76:79], v[32:47]
	global_store_dwordx2 v[96:97], v[0:1], off offset:64
	v_lshlrev_b32_e32 v0, 16, v216
	v_and_b32_e32 v1, 0xffff0000, v216
	v_lshlrev_b32_e32 v2, 16, v217
	v_and_b32_e32 v3, 0xffff0000, v217
	v_mul_f32_e32 v0, v20, v0
	v_mul_f32_e32 v1, v21, v1
	v_mul_f32_e32 v2, v22, v2
	v_mul_f32_e32 v3, v23, v3
	v_cvt_pk_bf16_f32 v0, v0, v1
	v_cvt_pk_bf16_f32 v1, v2, v3
	v_mfma_f32_32x32x16_bf16 v[32:47], v[134:137], v[72:75], v[32:47]
	global_store_dwordx2 v[96:97], v[0:1], off offset:80
	v_lshlrev_b32_e32 v0, 16, v218
	v_and_b32_e32 v1, 0xffff0000, v218
	v_lshlrev_b32_e32 v2, 16, v219
	v_and_b32_e32 v3, 0xffff0000, v219
	v_mul_f32_e32 v0, v24, v0
	v_mul_f32_e32 v1, v25, v1
	v_mul_f32_e32 v2, v26, v2
	v_mul_f32_e32 v3, v27, v3
	v_cvt_pk_bf16_f32 v0, v0, v1
	v_cvt_pk_bf16_f32 v1, v2, v3
	v_mfma_f32_32x32x16_bf16 v[32:47], v[80:83], v[68:71], v[32:47]
	global_store_dwordx2 v[96:97], v[0:1], off offset:96
	v_lshlrev_b32_e32 v0, 16, v220
	v_and_b32_e32 v1, 0xffff0000, v220
	v_lshlrev_b32_e32 v2, 16, v221
	v_and_b32_e32 v3, 0xffff0000, v221
	v_mul_f32_e32 v0, v28, v0
	v_mul_f32_e32 v1, v29, v1
	v_mul_f32_e32 v2, v30, v2
	v_mul_f32_e32 v3, v31, v3
	v_cvt_pk_bf16_f32 v0, v0, v1
	v_cvt_pk_bf16_f32 v1, v2, v3
	v_mfma_f32_32x32x16_bf16 v[32:47], v[98:101], v[64:67], v[32:47]
	global_store_dwordx2 v[96:97], v[0:1], off offset:112
	v_lshlrev_b32_e32 v0, 16, v222
	v_and_b32_e32 v1, 0xffff0000, v222
	v_lshlrev_b32_e32 v2, 16, v223
	v_and_b32_e32 v3, 0xffff0000, v223
	s_nop 5
	v_mul_f32_e32 v0, v32, v0
	v_mul_f32_e32 v1, v33, v1
	v_mul_f32_e32 v2, v34, v2
	v_mul_f32_e32 v3, v35, v3
	v_cvt_pk_bf16_f32 v0, v0, v1
	v_cvt_pk_bf16_f32 v1, v2, v3
	v_mfma_f32_32x32x16_bf16 v[48:63], v[110:113], v[92:95], v[48:63]
	global_store_dwordx2 v[96:97], v[0:1], off offset:128
	v_lshlrev_b32_e32 v0, 16, v224
	v_and_b32_e32 v1, 0xffff0000, v224
	v_lshlrev_b32_e32 v2, 16, v225
	v_and_b32_e32 v3, 0xffff0000, v225
	v_mul_f32_e32 v0, v36, v0
	v_mul_f32_e32 v1, v37, v1
	v_mul_f32_e32 v2, v38, v2
	v_mul_f32_e32 v3, v39, v3
	v_cvt_pk_bf16_f32 v0, v0, v1
	v_cvt_pk_bf16_f32 v1, v2, v3
	v_mfma_f32_32x32x16_bf16 v[48:63], v[138:141], v[76:79], v[48:63]
	global_store_dwordx2 v[96:97], v[0:1], off offset:144
	v_lshlrev_b32_e32 v0, 16, v226
	v_and_b32_e32 v1, 0xffff0000, v226
	v_lshlrev_b32_e32 v2, 16, v227
	v_and_b32_e32 v3, 0xffff0000, v227
	v_mul_f32_e32 v0, v40, v0
	v_mul_f32_e32 v1, v41, v1
	v_mul_f32_e32 v2, v42, v2
	v_mul_f32_e32 v3, v43, v3
	v_cvt_pk_bf16_f32 v0, v0, v1
	v_cvt_pk_bf16_f32 v1, v2, v3
	v_mfma_f32_32x32x16_bf16 v[48:63], v[142:145], v[72:75], v[48:63]
	global_store_dwordx2 v[96:97], v[0:1], off offset:160
	v_lshlrev_b32_e32 v0, 16, v228
	v_and_b32_e32 v1, 0xffff0000, v228
	v_lshlrev_b32_e32 v2, 16, v229
	v_and_b32_e32 v3, 0xffff0000, v229
	v_mul_f32_e32 v0, v44, v0
	v_mul_f32_e32 v1, v45, v1
	v_mul_f32_e32 v2, v46, v2
	v_mul_f32_e32 v3, v47, v3
	v_cvt_pk_bf16_f32 v0, v0, v1
	v_cvt_pk_bf16_f32 v1, v2, v3
	v_mfma_f32_32x32x16_bf16 v[48:63], v[84:87], v[68:71], v[48:63]
	global_store_dwordx2 v[96:97], v[0:1], off offset:176
	v_lshlrev_b32_e32 v0, 16, v230
	v_mfma_f32_32x32x16_bf16 v[48:63], v[102:105], v[64:67], v[48:63]
	v_and_b32_e32 v1, 0xffff0000, v230
	v_lshlrev_b32_e32 v2, 16, v231
	v_and_b32_e32 v3, 0xffff0000, v231
	s_nop 8
	v_mul_f32_e32 v0, v48, v0
	v_mul_f32_e32 v1, v49, v1
	v_mul_f32_e32 v2, v50, v2
	v_mul_f32_e32 v3, v51, v3
	v_cvt_pk_bf16_f32 v0, v0, v1
	v_cvt_pk_bf16_f32 v1, v2, v3
	s_nop 0
	global_store_dwordx2 v[96:97], v[0:1], off offset:192
	v_lshlrev_b32_e32 v0, 16, v232
	v_and_b32_e32 v1, 0xffff0000, v232
	v_lshlrev_b32_e32 v2, 16, v233
	v_and_b32_e32 v3, 0xffff0000, v233
	v_mul_f32_e32 v0, v52, v0
	v_mul_f32_e32 v1, v53, v1
	v_mul_f32_e32 v2, v54, v2
	v_mul_f32_e32 v3, v55, v3
	v_cvt_pk_bf16_f32 v0, v0, v1
	v_cvt_pk_bf16_f32 v1, v2, v3
	s_nop 0
	global_store_dwordx2 v[96:97], v[0:1], off offset:208
	v_lshlrev_b32_e32 v0, 16, v234
	v_and_b32_e32 v1, 0xffff0000, v234
	v_lshlrev_b32_e32 v2, 16, v235
	v_and_b32_e32 v3, 0xffff0000, v235
	v_mul_f32_e32 v0, v56, v0
	v_mul_f32_e32 v1, v57, v1
	v_mul_f32_e32 v2, v58, v2
	v_mul_f32_e32 v3, v59, v3
	v_cvt_pk_bf16_f32 v0, v0, v1
	v_cvt_pk_bf16_f32 v1, v2, v3
	s_nop 0
	global_store_dwordx2 v[96:97], v[0:1], off offset:224
	v_lshlrev_b32_e32 v0, 16, v236
	v_and_b32_e32 v1, 0xffff0000, v236
	v_lshlrev_b32_e32 v2, 16, v237
	v_and_b32_e32 v3, 0xffff0000, v237
	v_mul_f32_e32 v0, v60, v0
	v_mul_f32_e32 v1, v61, v1
	v_mul_f32_e32 v2, v62, v2
	v_mul_f32_e32 v3, v63, v3
	v_cvt_pk_bf16_f32 v0, v0, v1
	v_cvt_pk_bf16_f32 v1, v2, v3
	global_store_dwordx2 v[96:97], v[0:1], off offset:240
	s_waitcnt lgkmcnt(0)
	s_barrier
	s_cbranch_scc1 .LBB0_525
